# MLA attention QK: deeper K-fragment LDS read-ahead (8 reads up front + 4 as quads free, into registers dead during QK) so each fragment has >=5 MFMAs of latency cover; same reads and MFMA order
# speedup vs baseline: 1.0134x; 1.0134x over previous
; #define LAS __attribute__((address_space(3)))
; template <int DQK, int DV, bool HAS_BIAS>
; __device__ __forceinline__ void attn_tile(AttnState<DQK, DV>& st, const LAS unsigned char* Kt, const LAS unsigned char* Vt, int bias_mode, const LAS float* tab, int rel0, int nkeys, bool first, LAS float* wsf, int lane) {
;     ...
;     const LAS unsigned char* kp = Kt + q * PK + hi * 16;
;     bf16x8 ka[KS], kb[KS];
; #pragma unroll
;     for (int ks = 0; ks < KS; ++ks) { ka[ks] = *(const LAS bf16x8*)(kp + ks * 32); kb[ks] = *(const LAS bf16x8*)(kp + 32 * PK + ks * 32); }
;     if (HAS_BIAS && bias_mode == 2) {
;         asm volatile("" ::: "memory");
; #pragma unroll
;         for (int r = 0; r < 16; ++r) {
;             const int k = crow(r, hi);
;             const int i0 = min(max(rel0 + k + 128, 0), 191), i1 = min(max(rel0 + k + 160, 0), 191);
;             p0[r] = tab[i0] + st.negm[r]; p1[r] = tab[i1] + st.negm[r];
;         }
;         p0 = __builtin_amdgcn_mfma_f32_32x32x16_bf16(ka[0], st.qf[0], p0, 0, 0, 0);
;         p1 = __builtin_amdgcn_mfma_f32_32x32x16_bf16(kb[0], st.qf[0], p1, 0, 0, 0);
;     } else {
;         p0 = __builtin_amdgcn_mfma_f32_32x32x16_bf16(ka[0], st.qf[0], st.negm, 0, 0, 0);
;         p1 = __builtin_amdgcn_mfma_f32_32x32x16_bf16(kb[0], st.qf[0], st.negm, 0, 0, 0);
;     }
; #pragma unroll
;     for (int ks = 1; ks < KS; ++ks) {
;         p0 = __builtin_amdgcn_mfma_f32_32x32x16_bf16(ka[ks], st.qf[ks], p0, 0, 0, 0);
;         p1 = __builtin_amdgcn_mfma_f32_32x32x16_bf16(kb[ks], st.qf[ks], p1, 0, 0, 0);
;     }
;     const int q4 = (lane & 15) >> 2, blk = (lane >> 4) & 1, pp = lane & 3;
;     const LAS unsigned char* vp = Vt + (4 * hi + q4) * PV + (16 * blk + 4 * pp) * 2;
;     s16x4 vlo[2][4], vhi[2][4];
; #pragma unroll
;     for (int s4 = 0; s4 < 4; ++s4) { vlo[0][s4] = vtr(vp + (16 * s4) * PV); vhi[0][s4] = vtr(vp + (16 * s4 + 8) * PV); }
;     __builtin_amdgcn_sched_barrier(0);
;     if (nkeys < 64) {
; #pragma unroll
;         for (int r = 0; r < 16; ++r) { const int k = crow(r, hi); if (k >= nkeys) p0[r] = -1e30f; if (k + 32 >= nkeys) p1[r] = -1e30f; }
;     }
;     float mxa = __builtin_fmaxf(__builtin_fmaxf(p0[0], p0[1]), p1[0]), mxb = __builtin_fmaxf(__builtin_fmaxf(p0[2], p0[3]), p1[1]);
;     mxa = __builtin_fmaxf(__builtin_fmaxf(mxa, p1[2]), p1[3]);
; #pragma unroll
;     for (int r = 4; r < 16; r += 4) {
.LBB0_580:
	ds_read_b128 v[64:67], v162 offset:8192
	ds_read_b128 v[132:135], v162 offset:14848
	ds_read_b128 v[128:131], v162 offset:8224
	ds_read_b128 v[136:139], v162 offset:14880
	ds_read_b128 v[168:171], v162 offset:8256
	ds_read_b128 v[172:175], v162 offset:14912
	ds_read_b128 v[176:179], v162 offset:8288
	ds_read_b128 v[164:167], v162 offset:14944
	s_cmp_eq_u32 s58, 0
	s_cselect_b64 s[4:5], -1, 0
	s_waitcnt lgkmcnt(7)
	v_mfma_f32_32x32x16_bf16 v[48:63], v[64:67], v[100:103], v[32:47]
	s_cmp_lg_u32 s58, 0
	s_waitcnt lgkmcnt(6)
	v_mfma_f32_32x32x16_bf16 v[64:79], v[132:135], v[100:103], v[32:47]
	ds_read_b128 v[132:135], v162 offset:8320
	s_waitcnt lgkmcnt(6)
	v_mfma_f32_32x32x16_bf16 v[48:63], v[128:131], v[80:83], v[48:63]
	ds_read_b128 v[128:131], v162 offset:14976
	s_waitcnt lgkmcnt(6)
	v_mfma_f32_32x32x16_bf16 v[64:79], v[136:139], v[80:83], v[64:79]
	ds_read_b128 v[136:139], v162 offset:8352
	s_waitcnt lgkmcnt(6)
	v_mfma_f32_32x32x16_bf16 v[48:63], v[168:171], v[84:87], v[48:63]
	ds_read_b128 v[168:171], v162 offset:15008
	s_waitcnt lgkmcnt(6)
	v_mfma_f32_32x32x16_bf16 v[64:79], v[172:175], v[84:87], v[64:79]
	s_waitcnt lgkmcnt(5)
	v_mfma_f32_32x32x16_bf16 v[48:63], v[176:179], v[88:91], v[48:63]
	s_waitcnt lgkmcnt(4)
	v_mfma_f32_32x32x16_bf16 v[64:79], v[164:167], v[88:91], v[64:79]
	s_waitcnt lgkmcnt(3)
	v_mfma_f32_32x32x16_bf16 v[48:63], v[132:135], v[92:95], v[48:63]
	s_waitcnt lgkmcnt(2)
	v_mfma_f32_32x32x16_bf16 v[64:79], v[128:131], v[92:95], v[64:79]
	s_waitcnt lgkmcnt(1)
	v_mfma_f32_32x32x16_bf16 v[48:63], v[136:139], v[96:99], v[48:63]
	ds_read_b64_tr_b16 v[140:141], v163 offset:21504
	ds_read_b64_tr_b16 v[142:143], v163 offset:23040
	ds_read_b64_tr_b16 v[136:137], v163 offset:24576
	ds_read_b64_tr_b16 v[138:139], v163 offset:26112
	ds_read_b64_tr_b16 v[132:133], v163 offset:27648
	ds_read_b64_tr_b16 v[134:135], v163 offset:29184
	ds_read_b64_tr_b16 v[128:129], v163 offset:30720
	ds_read_b64_tr_b16 v[130:131], v163 offset:32256
	s_waitcnt lgkmcnt(8)
	v_mfma_f32_32x32x16_bf16 v[64:79], v[168:171], v[96:99], v[64:79]
	s_nop 1
	v_max_f32_e32 v152, v49, v49
	v_max_f32_e32 v164, v48, v48
	v_max_f32_e32 v152, v164, v152
	s_nop 6
	v_max3_f32 v164, v50, v51, v65
	v_max3_f32 v152, v152, v64, v66
	v_max3_f32 v152, v152, v67, v52
	v_max3_f32 v164, v164, v54, v55
	v_max3_f32 v152, v152, v53, v68
	v_max3_f32 v164, v164, v70, v71
	v_max3_f32 v152, v152, v69, v56
	v_max3_f32 v164, v164, v58, v59
	v_max3_f32 v152, v152, v57, v72
	v_max3_f32 v164, v164, v74, v75
	v_max3_f32 v152, v152, v73, v60
	v_max3_f32 v164, v164, v62, v63
	v_max3_f32 v152, v152, v61, v76
	v_max3_f32 v164, v164, v78, v79
	v_max3_f32 v152, v152, v77, v164
	v_mov_b32_e32 v164, v152
	s_nop 1
	v_permlane32_swap_b32_e32 v152, v164
	v_max_f32_e32 v164, v164, v164
	v_max_f32_e32 v152, v152, v152
	v_max_f32_e32 v152, v152, v164
	s_cbranch_scc0 .LBB0_595
	v_cmp_lt_f32_e32 vcc, s77, v152
	s_cmp_lg_u64 vcc, 0
	s_cselect_b64 s[38:39], -1, 0
	s_cbranch_execz .LBB0_596
	s_branch .LBB0_597

; #define LAS __attribute__((address_space(3)))
; template <int DQK, int DV, bool HAS_BIAS>
; __device__ __forceinline__ void attn_tile(AttnState<DQK, DV>& st, const LAS unsigned char* Kt, const LAS unsigned char* Vt, int bias_mode, const LAS float* tab, int rel0, int nkeys, bool first, LAS float* wsf, int lane) {
;     ...
;     const LAS unsigned char* kp = Kt + q * PK + hi * 16;
;     bf16x8 ka[KS], kb[KS];
; #pragma unroll
;     for (int ks = 0; ks < KS; ++ks) { ka[ks] = *(const LAS bf16x8*)(kp + ks * 32); kb[ks] = *(const LAS bf16x8*)(kp + 32 * PK + ks * 32); }
;     if (HAS_BIAS && bias_mode == 2) {
;         asm volatile("" ::: "memory");
; #pragma unroll
;         for (int r = 0; r < 16; ++r) {
;             const int k = crow(r, hi);
;             const int i0 = min(max(rel0 + k + 128, 0), 191), i1 = min(max(rel0 + k + 160, 0), 191);
;             p0[r] = tab[i0] + st.negm[r]; p1[r] = tab[i1] + st.negm[r];
;         }
;         p0 = __builtin_amdgcn_mfma_f32_32x32x16_bf16(ka[0], st.qf[0], p0, 0, 0, 0);
;         p1 = __builtin_amdgcn_mfma_f32_32x32x16_bf16(kb[0], st.qf[0], p1, 0, 0, 0);
;     } else {
;         p0 = __builtin_amdgcn_mfma_f32_32x32x16_bf16(ka[0], st.qf[0], st.negm, 0, 0, 0);
;         p1 = __builtin_amdgcn_mfma_f32_32x32x16_bf16(kb[0], st.qf[0], st.negm, 0, 0, 0);
;     }
; #pragma unroll
;     for (int ks = 1; ks < KS; ++ks) {
;         p0 = __builtin_amdgcn_mfma_f32_32x32x16_bf16(ka[ks], st.qf[ks], p0, 0, 0, 0);
;         p1 = __builtin_amdgcn_mfma_f32_32x32x16_bf16(kb[ks], st.qf[ks], p1, 0, 0, 0);
;     }
;     const int q4 = (lane & 15) >> 2, blk = (lane >> 4) & 1, pp = lane & 3;
;     const LAS unsigned char* vp = Vt + (4 * hi + q4) * PV + (16 * blk + 4 * pp) * 2;
;     s16x4 vlo[2][4], vhi[2][4];
; #pragma unroll
;     for (int s4 = 0; s4 < 4; ++s4) { vlo[0][s4] = vtr(vp + (16 * s4) * PV); vhi[0][s4] = vtr(vp + (16 * s4 + 8) * PV); }
;     __builtin_amdgcn_sched_barrier(0);
;     if (nkeys < 64) {
; #pragma unroll
;         for (int r = 0; r < 16; ++r) { const int k = crow(r, hi); if (k >= nkeys) p0[r] = -1e30f; if (k + 32 >= nkeys) p1[r] = -1e30f; }
;     }
;     float mxa = __builtin_fmaxf(__builtin_fmaxf(p0[0], p0[1]), p1[0]), mxb = __builtin_fmaxf(__builtin_fmaxf(p0[2], p0[3]), p1[1]);
;     mxa = __builtin_fmaxf(__builtin_fmaxf(mxa, p1[2]), p1[3]);
; #pragma unroll
;     for (int r = 4; r < 16; r += 4) {
.LBB0_585:
	ds_read_b128 v[64:67], v162 offset:33792
	ds_read_b128 v[132:135], v162 offset:40448
	ds_read_b128 v[128:131], v162 offset:33824
	ds_read_b128 v[136:139], v162 offset:40480
	ds_read_b128 v[168:171], v162 offset:33856
	ds_read_b128 v[172:175], v162 offset:40512
	ds_read_b128 v[176:179], v162 offset:33888
	ds_read_b128 v[164:167], v162 offset:40544
	s_waitcnt lgkmcnt(7)
	v_mfma_f32_32x32x16_bf16 v[48:63], v[64:67], v[100:103], v[32:47]
	s_waitcnt lgkmcnt(6)
	v_mfma_f32_32x32x16_bf16 v[64:79], v[132:135], v[100:103], v[32:47]
	ds_read_b128 v[132:135], v162 offset:33920
	s_waitcnt lgkmcnt(6)
	v_mfma_f32_32x32x16_bf16 v[48:63], v[128:131], v[80:83], v[48:63]
	ds_read_b128 v[128:131], v162 offset:40576
	s_waitcnt lgkmcnt(6)
	v_mfma_f32_32x32x16_bf16 v[64:79], v[136:139], v[80:83], v[64:79]
	ds_read_b128 v[136:139], v162 offset:33952
	s_waitcnt lgkmcnt(6)
	v_mfma_f32_32x32x16_bf16 v[48:63], v[168:171], v[84:87], v[48:63]
	ds_read_b128 v[168:171], v162 offset:40608
	s_waitcnt lgkmcnt(6)
	v_mfma_f32_32x32x16_bf16 v[64:79], v[172:175], v[84:87], v[64:79]
	s_waitcnt lgkmcnt(5)
	v_mfma_f32_32x32x16_bf16 v[48:63], v[176:179], v[88:91], v[48:63]
	s_waitcnt lgkmcnt(4)
	v_mfma_f32_32x32x16_bf16 v[64:79], v[164:167], v[88:91], v[64:79]
	s_waitcnt lgkmcnt(3)
	v_mfma_f32_32x32x16_bf16 v[48:63], v[132:135], v[92:95], v[48:63]
	s_waitcnt lgkmcnt(2)
	v_mfma_f32_32x32x16_bf16 v[64:79], v[128:131], v[92:95], v[64:79]
	s_waitcnt lgkmcnt(1)
	v_mfma_f32_32x32x16_bf16 v[48:63], v[136:139], v[96:99], v[48:63]
	ds_read_b64_tr_b16 v[140:141], v163 offset:47104
	ds_read_b64_tr_b16 v[142:143], v163 offset:48640
	ds_read_b64_tr_b16 v[136:137], v163 offset:50176
	ds_read_b64_tr_b16 v[138:139], v163 offset:51712
	ds_read_b64_tr_b16 v[132:133], v163 offset:53248
	ds_read_b64_tr_b16 v[134:135], v163 offset:54784
	ds_read_b64_tr_b16 v[128:129], v163 offset:56320
	ds_read_b64_tr_b16 v[130:131], v163 offset:57856
	s_waitcnt lgkmcnt(8)
	v_mfma_f32_32x32x16_bf16 v[64:79], v[168:171], v[96:99], v[64:79]
	s_nop 1
	v_max_f32_e32 v150, v49, v49
	v_max_f32_e32 v151, v48, v48
	v_max_f32_e32 v150, v151, v150
	s_nop 6
	v_max3_f32 v151, v50, v51, v65
	v_max3_f32 v150, v150, v64, v66
	v_max3_f32 v150, v150, v67, v52
	v_max3_f32 v151, v151, v54, v55
	v_max3_f32 v150, v150, v53, v68
	v_max3_f32 v151, v151, v70, v71
	v_max3_f32 v150, v150, v69, v56
	v_max3_f32 v151, v151, v58, v59
	v_max3_f32 v150, v150, v57, v72
	v_max3_f32 v151, v151, v74, v75
	v_max3_f32 v150, v150, v73, v60
	v_max3_f32 v151, v151, v62, v63
	v_max3_f32 v150, v150, v61, v76
	v_max3_f32 v151, v151, v78, v79
	v_max3_f32 v150, v150, v77, v151
	v_mov_b32_e32 v151, v150
	s_nop 1
	v_permlane32_swap_b32_e32 v150, v151
	v_max_f32_e32 v151, v151, v151
	v_max_f32_e32 v150, v150, v150
	v_max_f32_e32 v150, v150, v151
	v_cmp_lt_f32_e32 vcc, s77, v150
	s_cbranch_vccz .LBB0_589
	v_max_f32_e32 v32, v150, v150
	v_max_f32_e32 v150, 0, v32
	v_exp_f32_e64 v151, -v150
	s_and_saveexec_b64 s[4:5], s[2:3]
	ds_write_b32 v158, v151 offset:6144
	s_or_b64 exec, exec, s[4:5]
	ds_read_b128 v[164:167], v155 offset:6144
	ds_read_b128 v[168:171], v155 offset:6176
	ds_read_b128 v[172:175], v155 offset:6208
	ds_read_b128 v[176:179], v155 offset:6240
	v_add_f32_e32 v161, v161, v150
	v_xor_b32_e32 v32, 0x80000000, v161
	v_pk_add_f32 v[48:49], v[48:49], v[150:151] op_sel_hi:[1,0] neg_lo:[0,1] neg_hi:[0,1]
	v_pk_add_f32 v[64:65], v[64:65], v[150:151] op_sel_hi:[1,0] neg_lo:[0,1] neg_hi:[0,1]
	v_pk_add_f32 v[50:51], v[50:51], v[150:151] op_sel_hi:[1,0] neg_lo:[0,1] neg_hi:[0,1]
	v_pk_add_f32 v[66:67], v[66:67], v[150:151] op_sel_hi:[1,0] neg_lo:[0,1] neg_hi:[0,1]
	v_pk_add_f32 v[52:53], v[52:53], v[150:151] op_sel_hi:[1,0] neg_lo:[0,1] neg_hi:[0,1]
	v_pk_add_f32 v[68:69], v[68:69], v[150:151] op_sel_hi:[1,0] neg_lo:[0,1] neg_hi:[0,1]
	v_pk_add_f32 v[54:55], v[54:55], v[150:151] op_sel_hi:[1,0] neg_lo:[0,1] neg_hi:[0,1]
	v_pk_add_f32 v[70:71], v[70:71], v[150:151] op_sel_hi:[1,0] neg_lo:[0,1] neg_hi:[0,1]
	v_pk_add_f32 v[56:57], v[56:57], v[150:151] op_sel_hi:[1,0] neg_lo:[0,1] neg_hi:[0,1]
	v_pk_add_f32 v[72:73], v[72:73], v[150:151] op_sel_hi:[1,0] neg_lo:[0,1] neg_hi:[0,1]
	v_pk_add_f32 v[58:59], v[58:59], v[150:151] op_sel_hi:[1,0] neg_lo:[0,1] neg_hi:[0,1]
	v_pk_add_f32 v[74:75], v[74:75], v[150:151] op_sel_hi:[1,0] neg_lo:[0,1] neg_hi:[0,1]
	v_pk_add_f32 v[60:61], v[60:61], v[150:151] op_sel_hi:[1,0] neg_lo:[0,1] neg_hi:[0,1]
	v_pk_add_f32 v[76:77], v[76:77], v[150:151] op_sel_hi:[1,0] neg_lo:[0,1] neg_hi:[0,1]
	v_mov_b32_e32 v33, v32
	v_mov_b32_e32 v34, v32
	v_mov_b32_e32 v35, v32
	v_mov_b32_e32 v36, v32
	v_mov_b32_e32 v37, v32
	v_mov_b32_e32 v38, v32
	v_mov_b32_e32 v39, v32
	v_mov_b32_e32 v40, v32
	v_mov_b32_e32 v41, v32
	v_mov_b32_e32 v42, v32
	v_mov_b32_e32 v43, v32
	v_mov_b32_e32 v44, v32
	v_mov_b32_e32 v45, v32
	v_mov_b32_e32 v46, v32
	v_mov_b32_e32 v47, v32
	v_pk_add_f32 v[62:63], v[62:63], v[150:151] op_sel_hi:[1,0] neg_lo:[0,1] neg_hi:[0,1]
	v_pk_add_f32 v[78:79], v[78:79], v[150:151] op_sel_hi:[1,0] neg_lo:[0,1] neg_hi:[0,1]
	v_mul_f32_e32 v160, v160, v151
	s_waitcnt lgkmcnt(0)
	v_pk_mul_f32 v[30:31], v[30:31], v[178:179]
	v_pk_mul_f32 v[26:27], v[26:27], v[174:175]
	v_pk_mul_f32 v[22:23], v[22:23], v[170:171]
	v_pk_mul_f32 v[18:19], v[18:19], v[166:167]
	v_pk_mul_f32 v[28:29], v[28:29], v[176:177]
	v_pk_mul_f32 v[24:25], v[24:25], v[172:173]
	v_pk_mul_f32 v[20:21], v[20:21], v[168:169]
	v_pk_mul_f32 v[16:17], v[16:17], v[164:165]
	v_pk_mul_f32 v[14:15], v[14:15], v[178:179]
	v_pk_mul_f32 v[10:11], v[10:11], v[174:175]
	v_pk_mul_f32 v[6:7], v[6:7], v[170:171]
	v_pk_mul_f32 v[2:3], v[2:3], v[166:167]
	v_pk_mul_f32 v[12:13], v[12:13], v[176:177]
	v_pk_mul_f32 v[8:9], v[8:9], v[172:173]
	v_pk_mul_f32 v[4:5], v[4:5], v[168:169]
	v_pk_mul_f32 v[0:1], v[0:1], v[164:165]
